# attention rescale (rare) paths: 64 packed f32 broadcast multiplies replaced by scalar v_mul pairs
# baseline (speedup 1.0000x reference)
.Latt_rare0:
	v_mov_b32_e32 v180, v1
	s_nop 1
	v_permlane32_swap_b32_e32 v1, v180
	v_max_f32_e32 v1, v1, v180
	s_cmp_eq_u32 s57, 0
	s_cselect_b32 s71, 0xf149f2ca, 0
	v_max_f32_e64 v243, v1, s71
	v_max_f32_e32 v242, 0, v1
	v_exp_f32_e64 v242, -v242
	v_sub_f32_e32 v210, v210, v243
	v_sub_f32_e32 v211, v211, v243
	v_sub_f32_e32 v212, v212, v243
	v_sub_f32_e32 v213, v213, v243
	v_sub_f32_e32 v214, v214, v243
	v_sub_f32_e32 v215, v215, v243
	v_sub_f32_e32 v216, v216, v243
	v_sub_f32_e32 v217, v217, v243
	v_sub_f32_e32 v218, v218, v243
	v_sub_f32_e32 v219, v219, v243
	v_sub_f32_e32 v220, v220, v243
	v_sub_f32_e32 v221, v221, v243
	v_sub_f32_e32 v222, v222, v243
	v_sub_f32_e32 v223, v223, v243
	v_sub_f32_e32 v224, v224, v243
	v_sub_f32_e32 v225, v225, v243
	v_sub_f32_e32 v66, v66, v243
	v_sub_f32_e32 v67, v67, v243
	v_sub_f32_e32 v68, v68, v243
	v_sub_f32_e32 v69, v69, v243
	v_sub_f32_e32 v70, v70, v243
	v_sub_f32_e32 v71, v71, v243
	v_sub_f32_e32 v72, v72, v243
	v_sub_f32_e32 v73, v73, v243
	v_sub_f32_e32 v74, v74, v243
	v_sub_f32_e32 v75, v75, v243
	v_sub_f32_e32 v76, v76, v243
	v_sub_f32_e32 v77, v77, v243
	v_sub_f32_e32 v78, v78, v243
	v_sub_f32_e32 v79, v79, v243
	v_sub_f32_e32 v80, v80, v243
	v_sub_f32_e32 v81, v81, v243
	v_sub_f32_e32 v82, v82, v243
	v_sub_f32_e32 v83, v83, v243
	v_sub_f32_e32 v84, v84, v243
	v_sub_f32_e32 v85, v85, v243
	v_sub_f32_e32 v86, v86, v243
	v_sub_f32_e32 v87, v87, v243
	v_sub_f32_e32 v88, v88, v243
	v_sub_f32_e32 v89, v89, v243
	v_sub_f32_e32 v90, v90, v243
	v_sub_f32_e32 v91, v91, v243
	v_sub_f32_e32 v92, v92, v243
	v_sub_f32_e32 v93, v93, v243
	v_sub_f32_e32 v94, v94, v243
	v_sub_f32_e32 v95, v95, v243
	v_sub_f32_e32 v96, v96, v243
	v_sub_f32_e32 v97, v97, v243
	s_cmp_eq_u32 s57, 0
	s_cbranch_scc1 .Latt_common0
	v_mul_f32_e32 v173, v173, v242
	v_mul_f32_e32 v64, v242, v64
	v_mul_f32_e32 v65, v242, v65
	v_mul_f32_e32 v62, v242, v62
	v_mul_f32_e32 v63, v242, v63
	v_mul_f32_e32 v60, v242, v60
	v_mul_f32_e32 v61, v242, v61
	v_mul_f32_e32 v58, v242, v58
	v_mul_f32_e32 v59, v242, v59
	v_mul_f32_e32 v56, v242, v56
	v_mul_f32_e32 v57, v242, v57
	v_mul_f32_e32 v54, v242, v54
	v_mul_f32_e32 v55, v242, v55
	v_mul_f32_e32 v52, v242, v52
	v_mul_f32_e32 v53, v242, v53
	v_mul_f32_e32 v50, v242, v50
	v_mul_f32_e32 v51, v242, v51
	v_mul_f32_e32 v48, v242, v48
	v_mul_f32_e32 v49, v242, v49
	v_mul_f32_e32 v46, v242, v46
	v_mul_f32_e32 v47, v242, v47
	v_mul_f32_e32 v44, v242, v44
	v_mul_f32_e32 v45, v242, v45
	v_mul_f32_e32 v42, v242, v42
	v_mul_f32_e32 v43, v242, v43
	v_mul_f32_e32 v40, v242, v40
	v_mul_f32_e32 v41, v242, v41
	v_mul_f32_e32 v38, v242, v38
	v_mul_f32_e32 v39, v242, v39
	v_mul_f32_e32 v36, v242, v36
	v_mul_f32_e32 v37, v242, v37
	v_mul_f32_e32 v34, v242, v34
	v_mul_f32_e32 v35, v242, v35
	v_mul_f32_e32 v32, v242, v32
	v_mul_f32_e32 v33, v242, v33
	v_mul_f32_e32 v30, v242, v30
	v_mul_f32_e32 v31, v242, v31
	v_mul_f32_e32 v28, v242, v28
	v_mul_f32_e32 v29, v242, v29
	v_mul_f32_e32 v26, v242, v26
	v_mul_f32_e32 v27, v242, v27
	v_mul_f32_e32 v24, v242, v24
	v_mul_f32_e32 v25, v242, v25
	v_mul_f32_e32 v22, v242, v22
	v_mul_f32_e32 v23, v242, v23
	v_mul_f32_e32 v20, v242, v20
	v_mul_f32_e32 v21, v242, v21
	v_mul_f32_e32 v18, v242, v18
	v_mul_f32_e32 v19, v242, v19
	v_mul_f32_e32 v16, v242, v16
	v_mul_f32_e32 v17, v242, v17
	v_mul_f32_e32 v14, v242, v14
	v_mul_f32_e32 v15, v242, v15
	v_mul_f32_e32 v12, v242, v12
	v_mul_f32_e32 v13, v242, v13
	v_mul_f32_e32 v10, v242, v10
	v_mul_f32_e32 v11, v242, v11
	v_mul_f32_e32 v8, v242, v8
	v_mul_f32_e32 v9, v242, v9
	v_mul_f32_e32 v6, v242, v6
	v_mul_f32_e32 v7, v242, v7
	v_mul_f32_e32 v4, v242, v4
	v_mul_f32_e32 v5, v242, v5
	v_mul_f32_e32 v2, v242, v2
	v_mul_f32_e32 v3, v242, v3

.Latt_rare1:
	v_mov_b32_e32 v180, v1
	s_nop 1
	v_permlane32_swap_b32_e32 v1, v180
	v_max_f32_e32 v1, v1, v180
	v_max_f32_e32 v243, 0, v1
	v_max_f32_e32 v242, 0, v1
	v_exp_f32_e64 v242, -v242
	v_sub_f32_e32 v210, v210, v243
	v_sub_f32_e32 v211, v211, v243
	v_sub_f32_e32 v212, v212, v243
	v_sub_f32_e32 v213, v213, v243
	v_sub_f32_e32 v214, v214, v243
	v_sub_f32_e32 v215, v215, v243
	v_sub_f32_e32 v216, v216, v243
	v_sub_f32_e32 v217, v217, v243
	v_sub_f32_e32 v218, v218, v243
	v_sub_f32_e32 v219, v219, v243
	v_sub_f32_e32 v220, v220, v243
	v_sub_f32_e32 v221, v221, v243
	v_sub_f32_e32 v222, v222, v243
	v_sub_f32_e32 v223, v223, v243
	v_sub_f32_e32 v224, v224, v243
	v_sub_f32_e32 v225, v225, v243
	v_sub_f32_e32 v66, v66, v243
	v_sub_f32_e32 v67, v67, v243
	v_sub_f32_e32 v68, v68, v243
	v_sub_f32_e32 v69, v69, v243
	v_sub_f32_e32 v70, v70, v243
	v_sub_f32_e32 v71, v71, v243
	v_sub_f32_e32 v72, v72, v243
	v_sub_f32_e32 v73, v73, v243
	v_sub_f32_e32 v74, v74, v243
	v_sub_f32_e32 v75, v75, v243
	v_sub_f32_e32 v76, v76, v243
	v_sub_f32_e32 v77, v77, v243
	v_sub_f32_e32 v78, v78, v243
	v_sub_f32_e32 v79, v79, v243
	v_sub_f32_e32 v80, v80, v243
	v_sub_f32_e32 v81, v81, v243
	v_sub_f32_e32 v82, v82, v243
	v_sub_f32_e32 v83, v83, v243
	v_sub_f32_e32 v84, v84, v243
	v_sub_f32_e32 v85, v85, v243
	v_sub_f32_e32 v86, v86, v243
	v_sub_f32_e32 v87, v87, v243
	v_sub_f32_e32 v88, v88, v243
	v_sub_f32_e32 v89, v89, v243
	v_sub_f32_e32 v90, v90, v243
	v_sub_f32_e32 v91, v91, v243
	v_sub_f32_e32 v92, v92, v243
	v_sub_f32_e32 v93, v93, v243
	v_sub_f32_e32 v94, v94, v243
	v_sub_f32_e32 v95, v95, v243
	v_sub_f32_e32 v96, v96, v243
	v_sub_f32_e32 v97, v97, v243
	v_mul_f32_e32 v173, v173, v242
	v_mul_f32_e32 v64, v242, v64
	v_mul_f32_e32 v65, v242, v65
	v_mul_f32_e32 v62, v242, v62
	v_mul_f32_e32 v63, v242, v63
	v_mul_f32_e32 v60, v242, v60
	v_mul_f32_e32 v61, v242, v61
	v_mul_f32_e32 v58, v242, v58
	v_mul_f32_e32 v59, v242, v59
	v_mul_f32_e32 v56, v242, v56
	v_mul_f32_e32 v57, v242, v57
	v_mul_f32_e32 v54, v242, v54
	v_mul_f32_e32 v55, v242, v55
	v_mul_f32_e32 v52, v242, v52
	v_mul_f32_e32 v53, v242, v53
	v_mul_f32_e32 v50, v242, v50
	v_mul_f32_e32 v51, v242, v51
	v_mul_f32_e32 v48, v242, v48
	v_mul_f32_e32 v49, v242, v49
	v_mul_f32_e32 v46, v242, v46
	v_mul_f32_e32 v47, v242, v47
	v_mul_f32_e32 v44, v242, v44
	v_mul_f32_e32 v45, v242, v45
	v_mul_f32_e32 v42, v242, v42
	v_mul_f32_e32 v43, v242, v43
	v_mul_f32_e32 v40, v242, v40
	v_mul_f32_e32 v41, v242, v41
	v_mul_f32_e32 v38, v242, v38
	v_mul_f32_e32 v39, v242, v39
	v_mul_f32_e32 v36, v242, v36
	v_mul_f32_e32 v37, v242, v37
	v_mul_f32_e32 v34, v242, v34
	v_mul_f32_e32 v35, v242, v35
	v_mul_f32_e32 v32, v242, v32
	v_mul_f32_e32 v33, v242, v33
	v_mul_f32_e32 v30, v242, v30
	v_mul_f32_e32 v31, v242, v31
	v_mul_f32_e32 v28, v242, v28
	v_mul_f32_e32 v29, v242, v29
	v_mul_f32_e32 v26, v242, v26
	v_mul_f32_e32 v27, v242, v27
	v_mul_f32_e32 v24, v242, v24
	v_mul_f32_e32 v25, v242, v25
	v_mul_f32_e32 v22, v242, v22
	v_mul_f32_e32 v23, v242, v23
	v_mul_f32_e32 v20, v242, v20
	v_mul_f32_e32 v21, v242, v21
	v_mul_f32_e32 v18, v242, v18
	v_mul_f32_e32 v19, v242, v19
	v_mul_f32_e32 v16, v242, v16
	v_mul_f32_e32 v17, v242, v17
	v_mul_f32_e32 v14, v242, v14
	v_mul_f32_e32 v15, v242, v15
	v_mul_f32_e32 v12, v242, v12
	v_mul_f32_e32 v13, v242, v13
	v_mul_f32_e32 v10, v242, v10
	v_mul_f32_e32 v11, v242, v11
	v_mul_f32_e32 v8, v242, v8
	v_mul_f32_e32 v9, v242, v9
	v_mul_f32_e32 v6, v242, v6
	v_mul_f32_e32 v7, v242, v7
	v_mul_f32_e32 v4, v242, v4
	v_mul_f32_e32 v5, v242, v5
	v_mul_f32_e32 v2, v242, v2
	v_mul_f32_e32 v3, v242, v3
